# OUT (even layers) epilogue: the 16 residual/gate loads of each 8-tile group issued up front, counted waits
# speedup vs baseline: 1.0106x; 1.0038x over previous
.LBB0_1634:
	v_lshrrev_b32_e32 v36, 12, v40
	v_add_u32_e32 v36, 1, v36
	v_cndmask_b32_e64 v36, v36, 0, s[0:1]
	v_add_u32_e32 v40, s22, v36
	v_mov_b64_e32 v[36:37], s[20:21]
	v_mad_u64_u32 v[36:37], s[0:1], v40, s29, v[36:37]
	v_lshl_add_u64 v[44:45], v[36:37], 0, s[8:9]
	v_lshl_add_u64 v[46:47], v[34:35], 0, v[0:1]
	v_lshl_add_u64 v[40:41], v[44:45], 0, v[0:1]
	v_lshl_add_u64 v[38:39], v[38:39], 0, v[0:1]
	global_load_dwordx4 v[170:173], v[46:47], off
	global_load_dwordx4 v[204:207], v[40:41], off
	global_load_dwordx4 v[174:177], v[46:47], off offset:64
	global_load_dwordx4 v[216:219], v[40:41], off offset:64
	global_load_dwordx4 v[180:183], v[46:47], off offset:128
	global_load_dwordx4 v[226:229], v[40:41], off offset:128
	global_load_dwordx4 v[184:187], v[46:47], off offset:192
	global_load_dwordx4 v[230:233], v[40:41], off offset:192
	global_load_dwordx4 v[188:191], v[46:47], off offset:256
	global_load_dwordx4 v[234:237], v[40:41], off offset:256
	global_load_dwordx4 v[192:195], v[46:47], off offset:320
	global_load_dwordx4 v[238:241], v[40:41], off offset:320
	global_load_dwordx4 v[196:199], v[46:47], off offset:384
	global_load_dwordx4 v[242:245], v[40:41], off offset:384
	global_load_dwordx4 v[200:203], v[46:47], off offset:448
	global_load_dwordx4 v[246:249], v[40:41], off offset:448
	v_lshl_add_u64 v[48:49], v[44:45], 0, v[118:119]
	s_add_i32 s34, s34, s76
	s_add_i32 s23, s23, s95
	s_cmpk_gt_u32 s34, 0x5f
	s_waitcnt vmcnt(14)
	v_pk_fma_f32 v[32:33], v[32:33], v[206:207], v[172:173]
	v_pk_fma_f32 v[30:31], v[30:31], v[204:205], v[170:171]
	global_store_dwordx4 v[38:39], v[30:33], off
	s_nop 1
	s_nop 0
	v_lshl_add_u64 v[40:41], v[44:45], 0, v[122:123]
	s_waitcnt vmcnt(13)
	v_pk_fma_f32 v[28:29], v[28:29], v[218:219], v[176:177]
	v_pk_fma_f32 v[26:27], v[26:27], v[216:217], v[174:175]
	global_store_dwordx4 v[38:39], v[26:29], off offset:64
	s_nop 1
	s_nop 0
	v_lshl_add_u64 v[34:35], v[44:45], 0, v[124:125]
	s_waitcnt vmcnt(12)
	v_pk_fma_f32 v[24:25], v[24:25], v[228:229], v[182:183]
	v_pk_fma_f32 v[22:23], v[22:23], v[226:227], v[180:181]
	global_store_dwordx4 v[38:39], v[22:25], off offset:128
	s_nop 1
	s_nop 0
	v_lshl_add_u64 v[30:31], v[44:45], 0, v[114:115]
	s_waitcnt vmcnt(11)
	v_pk_fma_f32 v[20:21], v[20:21], v[232:233], v[186:187]
	v_pk_fma_f32 v[18:19], v[18:19], v[230:231], v[184:185]
	global_store_dwordx4 v[38:39], v[18:21], off offset:192
	s_nop 1
	s_nop 0
	v_lshl_add_u64 v[26:27], v[44:45], 0, v[110:111]
	s_waitcnt vmcnt(10)
	v_pk_fma_f32 v[16:17], v[16:17], v[236:237], v[190:191]
	v_pk_fma_f32 v[14:15], v[14:15], v[234:235], v[188:189]
	global_store_dwordx4 v[38:39], v[14:17], off offset:256
	s_nop 1
	s_nop 0
	v_lshl_add_u64 v[22:23], v[44:45], 0, v[106:107]
	s_waitcnt vmcnt(9)
	v_pk_fma_f32 v[12:13], v[12:13], v[240:241], v[194:195]
	v_pk_fma_f32 v[10:11], v[10:11], v[238:239], v[192:193]
	global_store_dwordx4 v[38:39], v[10:13], off offset:320
	s_nop 1
	s_nop 0
	v_lshl_add_u64 v[18:19], v[44:45], 0, v[102:103]
	s_waitcnt vmcnt(8)
	v_pk_fma_f32 v[8:9], v[8:9], v[244:245], v[198:199]
	v_pk_fma_f32 v[6:7], v[6:7], v[242:243], v[196:197]
	global_store_dwordx4 v[38:39], v[6:9], off offset:384
	s_nop 1
	s_nop 0
	s_waitcnt vmcnt(7)
	v_pk_fma_f32 v[4:5], v[4:5], v[248:249], v[202:203]
	v_pk_fma_f32 v[2:3], v[2:3], v[246:247], v[200:201]
	global_store_dwordx4 v[38:39], v[2:5], off offset:448
	s_nop 1
	s_cbranch_scc1 .LBB0_1662

.LBB0_1645:
	v_lshrrev_b32_e32 v0, 12, v0
	s_add_u32 s20, s90, s8
	v_add_u32_e32 v0, 1, v0
	s_addc_u32 s21, s91, s9
	v_cndmask_b32_e64 v0, v0, 0, s[0:1]
	v_lshrrev_b32_e32 v121, 2, v124
	v_add_u32_e32 v0, s22, v0
	v_mov_b64_e32 v[124:125], s[20:21]
	v_and_or_b32 v121, v121, 12, s10
	v_mad_u64_u32 v[124:125], s[0:1], v0, s29, v[124:125]
	s_mov_b64 s[8:9], 0x5700
	s_waitcnt vmcnt(9)
	v_lshl_add_u64 v[128:129], v[124:125], 0, s[8:9]
	v_lshlrev_b32_e32 v0, 2, v121
	s_waitcnt vmcnt(8)
	v_lshl_add_u64 v[134:135], v[122:123], 0, v[0:1]
	v_lshl_add_u64 v[126:127], v[128:129], 0, v[0:1]
	global_load_dwordx4 v[170:173], v[134:135], off
	global_load_dwordx4 v[204:207], v[126:127], off
	global_load_dwordx4 v[174:177], v[134:135], off offset:64
	global_load_dwordx4 v[216:219], v[126:127], off offset:64
	global_load_dwordx4 v[180:183], v[134:135], off offset:128
	global_load_dwordx4 v[226:229], v[126:127], off offset:128
	global_load_dwordx4 v[184:187], v[134:135], off offset:192
	global_load_dwordx4 v[230:233], v[126:127], off offset:192
	global_load_dwordx4 v[188:191], v[134:135], off offset:256
	global_load_dwordx4 v[234:237], v[126:127], off offset:256
	global_load_dwordx4 v[192:195], v[134:135], off offset:320
	global_load_dwordx4 v[238:241], v[126:127], off offset:320
	global_load_dwordx4 v[196:199], v[134:135], off offset:384
	global_load_dwordx4 v[242:245], v[126:127], off offset:384
	global_load_dwordx4 v[200:203], v[134:135], off offset:448
	global_load_dwordx4 v[246:249], v[126:127], off offset:448
	v_lshl_add_u64 v[126:127], v[118:119], 0, v[0:1]
	v_or_b32_e32 v118, 16, v121
	v_lshlrev_b32_e32 v118, 2, v118
	v_mov_b32_e32 v119, v1
	s_and_b64 vcc, exec, s[40:41]
	s_waitcnt vmcnt(14)
	v_pk_fma_f32 v[124:125], v[168:169], v[206:207], v[172:173]
	v_pk_fma_f32 v[122:123], v[166:167], v[204:205], v[170:171]
	global_store_dwordx4 v[126:127], v[122:125], off
	s_nop 1
	v_lshl_add_u64 v[136:137], v[128:129], 0, v[118:119]
	s_nop 0
	s_waitcnt vmcnt(13)
	v_pk_fma_f32 v[124:125], v[148:149], v[218:219], v[176:177]
	v_pk_fma_f32 v[122:123], v[146:147], v[216:217], v[174:175]
	global_store_dwordx4 v[126:127], v[122:125], off offset:64
	s_nop 1
	s_nop 0
	v_or_b32_e32 v122, 32, v121
	v_lshlrev_b32_e32 v122, 2, v122
	v_mov_b32_e32 v123, v1
	v_lshl_add_u64 v[124:125], v[128:129], 0, v[122:123]
	v_or_b32_e32 v124, 48, v121
	v_lshlrev_b32_e32 v124, 2, v124
	v_mov_b32_e32 v125, v1
	s_waitcnt vmcnt(12)
	v_pk_fma_f32 v[132:133], v[132:133], v[228:229], v[182:183]
	v_pk_fma_f32 v[130:131], v[130:131], v[226:227], v[180:181]
	global_store_dwordx4 v[126:127], v[130:133], off offset:128
	s_nop 1
	v_lshl_add_u64 v[136:137], v[128:129], 0, v[124:125]
	s_nop 0
	s_waitcnt vmcnt(11)
	v_pk_fma_f32 v[116:117], v[116:117], v[232:233], v[186:187]
	v_pk_fma_f32 v[114:115], v[114:115], v[230:231], v[184:185]
	global_store_dwordx4 v[126:127], v[114:117], off offset:192
	s_nop 1
	s_nop 0
	v_or_b32_e32 v114, 64, v121
	v_lshlrev_b32_e32 v114, 2, v114
	v_mov_b32_e32 v115, v1
	v_lshl_add_u64 v[116:117], v[128:129], 0, v[114:115]
	s_waitcnt vmcnt(10)
	v_pk_fma_f32 v[112:113], v[112:113], v[236:237], v[190:191]
	v_pk_fma_f32 v[110:111], v[110:111], v[234:235], v[188:189]
	global_store_dwordx4 v[126:127], v[110:113], off offset:256
	s_nop 1
	s_nop 0
	v_or_b32_e32 v110, 0x50, v121
	v_lshlrev_b32_e32 v110, 2, v110
	v_mov_b32_e32 v111, v1
	v_lshl_add_u64 v[112:113], v[128:129], 0, v[110:111]
	s_waitcnt vmcnt(9)
	v_pk_fma_f32 v[108:109], v[108:109], v[240:241], v[194:195]
	v_pk_fma_f32 v[106:107], v[106:107], v[238:239], v[192:193]
	global_store_dwordx4 v[126:127], v[106:109], off offset:320
	s_nop 1
	s_nop 0
	v_or_b32_e32 v106, 0x60, v121
	v_lshlrev_b32_e32 v106, 2, v106
	v_mov_b32_e32 v107, v1
	v_lshl_add_u64 v[108:109], v[128:129], 0, v[106:107]
	s_waitcnt vmcnt(8)
	v_pk_fma_f32 v[104:105], v[104:105], v[244:245], v[198:199]
	v_pk_fma_f32 v[102:103], v[102:103], v[242:243], v[196:197]
	global_store_dwordx4 v[126:127], v[102:105], off offset:384
	s_nop 1
	s_nop 0
	v_or_b32_e32 v102, 0x70, v121
	v_lshlrev_b32_e32 v102, 2, v102
	v_mov_b32_e32 v103, v1
	v_lshl_add_u64 v[104:105], v[128:129], 0, v[102:103]
	s_waitcnt vmcnt(7)
	v_pk_fma_f32 v[100:101], v[100:101], v[248:249], v[202:203]
	v_pk_fma_f32 v[98:99], v[98:99], v[246:247], v[200:201]
	global_store_dwordx4 v[126:127], v[98:101], off offset:448
	s_nop 1
	s_nop 1
	v_or_b32_e32 v100, 16, v120
	v_ashrrev_i32_e32 v101, 31, v100
	v_lshlrev_b64 v[104:105], 12, v[100:101]
	v_lshl_add_u64 v[104:105], s[88:89], 0, v[104:105]
	v_cmp_gt_i32_e64 s[42:43], s68, v100
	v_cmp_lt_i32_e64 s[0:1], s11, v100
	v_add_u32_e32 v98, 0xffffe010, v120
	v_mov_b64_e32 v[108:109], v[104:105]
	s_cbranch_vccnz .LBB0_1651
	s_and_saveexec_b64 s[8:9], s[0:1]
	s_xor_b64 s[0:1], exec, s[8:9]
	s_cbranch_execz .LBB0_1648
	v_mov_b32_e32 v99, v1
	v_readlane_b32 s44, v252, 8
	v_lshlrev_b64 v[100:101], 12, v[98:99]
	v_readlane_b32 s46, v252, 10
	v_readlane_b32 s47, v252, 11
	v_readlane_b32 s45, v252, 9
	v_readlane_b32 s48, v252, 12
	v_lshl_add_u64 v[108:109], s[46:47], 0, v[100:101]
	v_readlane_b32 s49, v252, 13
	v_readlane_b32 s50, v252, 14
	v_readlane_b32 s51, v252, 15
	v_readlane_b32 s52, v252, 16
	v_readlane_b32 s53, v252, 17
	v_readlane_b32 s54, v252, 18
	v_readlane_b32 s55, v252, 19
	v_readlane_b32 s56, v252, 20
	v_readlane_b32 s57, v252, 21
	v_readlane_b32 s58, v252, 22
	v_readlane_b32 s59, v252, 23

.LBB0_1651:
	v_lshrrev_b32_e32 v98, 12, v98
	v_add_u32_e32 v98, 1, v98
	v_cndmask_b32_e64 v98, v98, 0, s[42:43]
	v_add_u32_e32 v100, s22, v98
	v_mov_b64_e32 v[98:99], s[20:21]
	v_mad_u64_u32 v[98:99], s[0:1], v100, s29, v[98:99]
	v_lshl_add_u64 v[98:99], v[98:99], 0, s[8:9]
	v_lshl_add_u64 v[100:101], v[108:109], 0, v[0:1]
	v_lshl_add_u64 v[108:109], v[98:99], 0, v[0:1]
	global_load_dwordx4 v[170:173], v[100:101], off
	global_load_dwordx4 v[204:207], v[108:109], off
	global_load_dwordx4 v[174:177], v[100:101], off offset:64
	global_load_dwordx4 v[216:219], v[108:109], off offset:64
	global_load_dwordx4 v[180:183], v[100:101], off offset:128
	global_load_dwordx4 v[226:229], v[108:109], off offset:128
	global_load_dwordx4 v[184:187], v[100:101], off offset:192
	global_load_dwordx4 v[230:233], v[108:109], off offset:192
	global_load_dwordx4 v[188:191], v[100:101], off offset:256
	global_load_dwordx4 v[234:237], v[108:109], off offset:256
	global_load_dwordx4 v[192:195], v[100:101], off offset:320
	global_load_dwordx4 v[238:241], v[108:109], off offset:320
	global_load_dwordx4 v[196:199], v[100:101], off offset:384
	global_load_dwordx4 v[242:245], v[108:109], off offset:384
	global_load_dwordx4 v[200:203], v[100:101], off offset:448
	global_load_dwordx4 v[246:249], v[108:109], off offset:448
	s_and_b64 vcc, exec, s[40:41]
	s_waitcnt vmcnt(14)
	v_pk_fma_f32 v[128:129], v[96:97], v[206:207], v[172:173]
	v_pk_fma_f32 v[126:127], v[94:95], v[204:205], v[170:171]
	v_lshl_add_u64 v[94:95], v[104:105], 0, v[0:1]
	global_store_dwordx4 v[94:95], v[126:129], off
	s_nop 1
	v_lshl_add_u64 v[96:97], v[98:99], 0, v[118:119]
	v_lshl_add_u64 v[96:97], v[98:99], 0, v[122:123]
	s_waitcnt vmcnt(13)
	v_pk_fma_f32 v[92:93], v[92:93], v[218:219], v[176:177]
	v_pk_fma_f32 v[90:91], v[90:91], v[216:217], v[174:175]
	global_store_dwordx4 v[94:95], v[90:93], off offset:64
	s_nop 1
	s_nop 0
	s_waitcnt vmcnt(12)
	v_pk_fma_f32 v[88:89], v[88:89], v[228:229], v[182:183]
	v_pk_fma_f32 v[86:87], v[86:87], v[226:227], v[180:181]
	global_store_dwordx4 v[94:95], v[86:89], off offset:128
	s_nop 1
	v_lshl_add_u64 v[90:91], v[98:99], 0, v[124:125]
	s_nop 0
	s_waitcnt vmcnt(11)
	v_pk_fma_f32 v[84:85], v[84:85], v[232:233], v[186:187]
	v_pk_fma_f32 v[82:83], v[82:83], v[230:231], v[184:185]
	global_store_dwordx4 v[94:95], v[82:85], off offset:192
	s_nop 1
	v_lshl_add_u64 v[86:87], v[98:99], 0, v[114:115]
	s_nop 0
	s_waitcnt vmcnt(10)
	v_pk_fma_f32 v[80:81], v[80:81], v[236:237], v[190:191]
	v_pk_fma_f32 v[78:79], v[78:79], v[234:235], v[188:189]
	global_store_dwordx4 v[94:95], v[78:81], off offset:256
	s_nop 1
	v_lshl_add_u64 v[82:83], v[98:99], 0, v[110:111]
	s_nop 0
	s_waitcnt vmcnt(9)
	v_pk_fma_f32 v[76:77], v[76:77], v[240:241], v[194:195]
	v_pk_fma_f32 v[74:75], v[74:75], v[238:239], v[192:193]
	global_store_dwordx4 v[94:95], v[74:77], off offset:320
	s_nop 1
	v_lshl_add_u64 v[78:79], v[98:99], 0, v[106:107]
	s_nop 0
	s_waitcnt vmcnt(8)
	v_pk_fma_f32 v[72:73], v[72:73], v[244:245], v[198:199]
	v_pk_fma_f32 v[70:71], v[70:71], v[242:243], v[196:197]
	global_store_dwordx4 v[94:95], v[70:73], off offset:384
	s_nop 1
	v_lshl_add_u64 v[74:75], v[98:99], 0, v[102:103]
	s_nop 0
	s_waitcnt vmcnt(7)
	v_pk_fma_f32 v[66:67], v[66:67], v[246:247], v[200:201]
	v_or_b32_e32 v70, 32, v120
	v_pk_fma_f32 v[68:69], v[68:69], v[248:249], v[202:203]
	v_ashrrev_i32_e32 v71, 31, v70
	global_store_dwordx4 v[94:95], v[66:69], off offset:448
	s_nop 1
	v_cmp_gt_i32_e64 s[42:43], s68, v70
	v_cmp_lt_i32_e64 s[0:1], s11, v70
	v_lshlrev_b64 v[66:67], 12, v[70:71]
	v_lshl_add_u64 v[66:67], s[88:89], 0, v[66:67]
	v_add_u32_e32 v68, 0xffffe020, v120
	v_mov_b64_e32 v[72:73], v[66:67]
	s_cbranch_vccnz .LBB0_1657
	s_and_saveexec_b64 s[8:9], s[0:1]
	s_xor_b64 s[0:1], exec, s[8:9]
	s_cbranch_execz .LBB0_1654
	v_mov_b32_e32 v69, v1
	v_readlane_b32 s44, v252, 8
	v_lshlrev_b64 v[70:71], 12, v[68:69]
	v_readlane_b32 s46, v252, 10
	v_readlane_b32 s47, v252, 11
	v_readlane_b32 s45, v252, 9
	v_readlane_b32 s48, v252, 12
	v_lshl_add_u64 v[72:73], s[46:47], 0, v[70:71]
	v_readlane_b32 s49, v252, 13
	v_readlane_b32 s50, v252, 14
	v_readlane_b32 s51, v252, 15
	v_readlane_b32 s52, v252, 16
	v_readlane_b32 s53, v252, 17
	v_readlane_b32 s54, v252, 18
	v_readlane_b32 s55, v252, 19
	v_readlane_b32 s56, v252, 20
	v_readlane_b32 s57, v252, 21
	v_readlane_b32 s58, v252, 22
	v_readlane_b32 s59, v252, 23

.LBB0_1657:
	v_lshrrev_b32_e32 v68, 12, v68
	v_add_u32_e32 v68, 1, v68
	v_cndmask_b32_e64 v68, v68, 0, s[42:43]
	v_add_u32_e32 v70, s22, v68
	v_mov_b64_e32 v[68:69], s[20:21]
	v_mad_u64_u32 v[68:69], s[0:1], v70, s29, v[68:69]
	v_lshl_add_u64 v[76:77], v[68:69], 0, s[8:9]
	v_lshl_add_u64 v[78:79], v[72:73], 0, v[0:1]
	v_lshl_add_u64 v[72:73], v[76:77], 0, v[0:1]
	v_lshl_add_u64 v[80:81], v[66:67], 0, v[0:1]
	global_load_dwordx4 v[170:173], v[78:79], off
	global_load_dwordx4 v[204:207], v[72:73], off
	global_load_dwordx4 v[174:177], v[78:79], off offset:64
	global_load_dwordx4 v[216:219], v[72:73], off offset:64
	global_load_dwordx4 v[180:183], v[78:79], off offset:128
	global_load_dwordx4 v[226:229], v[72:73], off offset:128
	global_load_dwordx4 v[184:187], v[78:79], off offset:192
	global_load_dwordx4 v[230:233], v[72:73], off offset:192
	global_load_dwordx4 v[188:191], v[78:79], off offset:256
	global_load_dwordx4 v[234:237], v[72:73], off offset:256
	global_load_dwordx4 v[192:195], v[78:79], off offset:320
	global_load_dwordx4 v[238:241], v[72:73], off offset:320
	global_load_dwordx4 v[196:199], v[78:79], off offset:384
	global_load_dwordx4 v[242:245], v[72:73], off offset:384
	global_load_dwordx4 v[200:203], v[78:79], off offset:448
	global_load_dwordx4 v[246:249], v[72:73], off offset:448
	v_mov_b32_e32 v119, v1
	v_lshl_add_u64 v[66:67], v[76:77], 0, v[118:119]
	v_mov_b32_e32 v123, v1
	v_mov_b32_e32 v125, v1
	v_mov_b32_e32 v115, v1
	v_mov_b32_e32 v111, v1
	v_mov_b32_e32 v107, v1
	v_mov_b32_e32 v103, v1
	s_and_b64 vcc, exec, s[40:41]
	s_waitcnt vmcnt(14)
	v_pk_fma_f32 v[64:65], v[64:65], v[206:207], v[172:173]
	v_pk_fma_f32 v[62:63], v[62:63], v[204:205], v[170:171]
	global_store_dwordx4 v[80:81], v[62:65], off
	s_nop 1
	s_nop 0
	v_lshl_add_u64 v[70:71], v[76:77], 0, v[122:123]
	s_waitcnt vmcnt(13)
	v_pk_fma_f32 v[60:61], v[60:61], v[218:219], v[176:177]
	v_pk_fma_f32 v[58:59], v[58:59], v[216:217], v[174:175]
	global_store_dwordx4 v[80:81], v[58:61], off offset:64
	s_nop 1
	s_nop 0
	v_lshl_add_u64 v[66:67], v[76:77], 0, v[124:125]
	s_waitcnt vmcnt(12)
	v_pk_fma_f32 v[56:57], v[56:57], v[228:229], v[182:183]
	v_pk_fma_f32 v[54:55], v[54:55], v[226:227], v[180:181]
	global_store_dwordx4 v[80:81], v[54:57], off offset:128
	s_nop 1
	s_nop 0
	v_lshl_add_u64 v[62:63], v[76:77], 0, v[114:115]
	s_waitcnt vmcnt(11)
	v_pk_fma_f32 v[52:53], v[52:53], v[232:233], v[186:187]
	v_pk_fma_f32 v[50:51], v[50:51], v[230:231], v[184:185]
	global_store_dwordx4 v[80:81], v[50:53], off offset:192
	s_nop 1
	s_nop 0
	v_lshl_add_u64 v[58:59], v[76:77], 0, v[110:111]
	s_waitcnt vmcnt(10)
	v_pk_fma_f32 v[48:49], v[48:49], v[236:237], v[190:191]
	v_pk_fma_f32 v[46:47], v[46:47], v[234:235], v[188:189]
	global_store_dwordx4 v[80:81], v[46:49], off offset:256
	s_nop 1
	s_nop 0
	v_lshl_add_u64 v[54:55], v[76:77], 0, v[106:107]
	s_waitcnt vmcnt(9)
	v_pk_fma_f32 v[44:45], v[44:45], v[240:241], v[194:195]
	v_pk_fma_f32 v[42:43], v[42:43], v[238:239], v[192:193]
	global_store_dwordx4 v[80:81], v[42:45], off offset:320
	s_nop 1
	s_nop 0
	v_lshl_add_u64 v[50:51], v[76:77], 0, v[102:103]
	s_waitcnt vmcnt(8)
	v_pk_fma_f32 v[40:41], v[40:41], v[244:245], v[198:199]
	v_pk_fma_f32 v[38:39], v[38:39], v[242:243], v[196:197]
	global_store_dwordx4 v[80:81], v[38:41], off offset:384
	s_nop 1
	s_nop 0
	v_or_b32_e32 v42, 48, v120
	v_ashrrev_i32_e32 v43, 31, v42
	v_lshlrev_b64 v[38:39], 12, v[42:43]
	v_lshl_add_u64 v[38:39], s[88:89], 0, v[38:39]
	v_add_u32_e32 v40, 0xffffe030, v120
	v_cmp_gt_i32_e64 s[0:1], s68, v42
	v_cmp_lt_i32_e64 s[40:41], s11, v42
	s_waitcnt vmcnt(7)
	v_pk_fma_f32 v[36:37], v[36:37], v[248:249], v[202:203]
	v_pk_fma_f32 v[34:35], v[34:35], v[246:247], v[200:201]
	global_store_dwordx4 v[80:81], v[34:37], off offset:448
	s_nop 1
	s_nop 1
	v_mov_b64_e32 v[34:35], v[38:39]
	s_cbranch_vccnz .LBB0_1634
	s_and_saveexec_b64 s[8:9], s[40:41]
	s_xor_b64 s[8:9], exec, s[8:9]
	s_cbranch_execz .LBB0_1660
	v_mov_b32_e32 v41, v1
	v_readlane_b32 s40, v252, 8
	v_lshlrev_b64 v[34:35], 12, v[40:41]
	v_readlane_b32 s42, v252, 10
	v_readlane_b32 s43, v252, 11
	v_readlane_b32 s41, v252, 9
	v_readlane_b32 s44, v252, 12
	v_lshl_add_u64 v[34:35], s[42:43], 0, v[34:35]
	v_readlane_b32 s45, v252, 13
	v_readlane_b32 s46, v252, 14
	v_readlane_b32 s47, v252, 15
	v_readlane_b32 s48, v252, 16
	v_readlane_b32 s49, v252, 17
	v_readlane_b32 s50, v252, 18
	v_readlane_b32 s51, v252, 19
	v_readlane_b32 s52, v252, 20
	v_readlane_b32 s53, v252, 21
	v_readlane_b32 s54, v252, 22
	v_readlane_b32 s55, v252, 23
